# diff loop: first two K-fragment LDS reads issued at the loop head right behind the barrier (before global loads and the active test)
# baseline (speedup 1.0000x reference)
; #define LAS __attribute__((address_space(3)))
; __device__ __forceinline__ f32x16 mfma32(bf16x8 a, bf16x8 b, f32x16 c) { return __builtin_amdgcn_mfma_f32_32x32x16_bf16(a, b, c, 0, 0, 0); }
; template <int MODE, int DK, bool PASS2> ...
;     ...
;         const int jn = (MODE == M_SLC) ? next_sel(un, j, tile_hi) : (MODE == M_FOX ? j - 1 : j + 1);
;         const bool has = (MODE == M_FOX) ? (jn >= tile_lo) : (jn <= tile_hi);
;         if (has) load_tile(jn);
;         bool dead = false;
;         {
;             const int kv0 = j * 64;
;             const int pos_min = (MODE == M_CMP) ? 16 * kv0 + 31 : kv0;
;             const int pos_max = (MODE == M_CMP) ? 16 * (kv0 + 63) + 31 : kv0 + 63;
;             bool active = pos_min <= t_wmax;
;             if (MODE == M_WIN) active = active && (t_wmin - pos_max < 512);
;             bool selbit = true;
;             if (MODE == M_SLC) {
;                 selbit = ((((const LAS unsigned*)impw)[j >> 5] >> (j & 31)) & 1u) != 0u;
;                 active = active && (__builtin_amdgcn_ballot_w64(selbit) != 0ull);
;             }
;             if (active) {
;                 f32x16 s0, s1;
;                 if (MODE == M_FOX) {
;                     const LAS float* ct = (const LAS float*)(lds + F_CT + buf * 256) + 8 * g;
; #pragma unroll
;                     for (int q4 = 0; q4 < 4; ++q4) {
;                         const f32x4 a = *(const LAS f32x4*)(ct + (q4 >> 1) * 16 + (q4 & 1) * 4), b = *(const LAS f32x4*)(ct + 32 + (q4 >> 1) * 16 + (q4 & 1) * 4);
; #pragma unroll
;                         for (int e = 0; e < 4; ++e) { s0[q4 * 4 + e] = a[e]; s1[q4 * 4 + e] = b[e]; }
;                     }
;                 } else { s0 = (f32x16)(0.f); s1 = (f32x16)(0.f); }
;                 const LAS unsigned char* kb = lds + F_KB0 + buf * F_KBS + g * 16 + prow * KSTR;
;                 __builtin_amdgcn_s_setprio(1);
; #pragma unroll
;                 for (int kk = 0; kk < DK / 16; ++kk) {
;                     const bf16x8 a0 = *(const LAS bf16x8*)(kb + kk * 32);
;                     const bf16x8 a1 = *(const LAS bf16x8*)(kb + 32 * KSTR + kk * 32);
;                     s0 = mfma32(a0, qf[kk], s0); s1 = mfma32(a1, qf[kk], s1);
.LBB0_2127:
	s_mul_i32 s4, s58, 0x4400
	v_add_u32_e32 v16, s4, v202
	ds_read_b128 v[4:7], v16
	ds_read_b128 v[8:11], v16 offset:32
	s_cmp_lt_i32 s59, s55
	s_cselect_b64 s[24:25], -1, 0
	s_cmp_ge_i32 s59, s55
	s_cbranch_scc1 .LBB0_2130
	global_load_dwordx4 v[130:133], v205, s[22:23]
	global_load_dwordx4 v[134:137], v204, s[16:17]
	global_load_dwordx4 v[138:141], v203, s[16:17]
	s_sub_i32 s4, s57, 63
	v_cmp_le_i32_e32 vcc, s4, v195
	s_and_saveexec_b64 s[26:27], vcc
	s_cbranch_execnz .LBB0_2131

; #define LAS __attribute__((address_space(3)))
; __device__ __forceinline__ float fexp2(float x) { return __builtin_amdgcn_exp2f(x); }
; __device__ __forceinline__ float fmax3(float a, float b, float c) { float d; asm("v_max3_f32 %0, %1, %2, %3" : "=v"(d) : "v"(a), "v"(b), "v"(c)); return d; }
; __device__ __forceinline__ f32x16 mfma32(bf16x8 a, bf16x8 b, f32x16 c) { return __builtin_amdgcn_mfma_f32_32x32x16_bf16(a, b, c, 0, 0, 0); }
; template <int MODE, int DK, bool PASS2> ...
;     ...
;                 const LAS unsigned char* kb = lds + F_KB0 + buf * F_KBS + g * 16 + prow * KSTR;
;                 __builtin_amdgcn_s_setprio(1);
; #pragma unroll
;                 for (int kk = 0; kk < DK / 16; ++kk) {
;                     const bf16x8 a0 = *(const LAS bf16x8*)(kb + kk * 32);
;                     const bf16x8 a1 = *(const LAS bf16x8*)(kb + 32 * KSTR + kk * 32);
;                     s0 = mfma32(a0, qf[kk], s0); s1 = mfma32(a1, qf[kk], s1);
;                 }
;                 __builtin_amdgcn_s_setprio(0);
;                 const bool need_causal = pos_max > t_wmin;
;                 const bool need_bias = (MODE != M_FOX) && ((t_wmin - pos_max) < 128);
;                 const bool need_win = (MODE == M_WIN) && (t_wmax - pos_min >= 512);
;                 if (!PASS2 && !(need_causal || need_bias || need_win)) {
;                     float mx = fmaxf(s0[0], s1[0]);
; #pragma unroll
;                     for (int r = 1; r < 16; ++r) mx = fmax3(mx, s0[r], s1[r]);
;                     if (MODE == M_SLC) mx = selbit ? mx : NEG;
;                     mx = xhalf_max(mx);
;                     const float mxs = mx * sl2;
;                     const float mn = (mxs > m_run + 8.0f) ? mxs : m_run;
;                     const float alpha = fexp2(m_run - mn);
;                     m_run = mn;
;                     float nm = -mn;
;                     if (MODE == M_SLC) nm = selbit ? nm : -__builtin_inff();
;                     float ps0 = 0.f, ps1 = 0.f;
; #pragma unroll
;                     for (int r = 0; r < 16; ++r) {
;                         s0[r] = fexp2(__builtin_fmaf(s0[r], sl2, nm)); s1[r] = fexp2(__builtin_fmaf(s1[r], sl2, nm));
;                         ps0 += s0[r]; ps1 += s1[r];
;                     }
;                     l_run = l_run * alpha + (ps0 + ps1);
;                     if (__builtin_amdgcn_ballot_w64(alpha != 1.0f) != 0ull) {
.LBB0_2131:
	s_setprio 1
	s_waitcnt lgkmcnt(1)
	v_mfma_f32_32x32x16_bf16 v[82:97], v[4:7], v[114:117], 0
	ds_read_b128 v[4:7], v16 offset:4608
	ds_read_b128 v[12:15], v16 offset:4640
	s_waitcnt lgkmcnt(1)
	v_mfma_f32_32x32x16_bf16 v[98:113], v[4:7], v[114:117], 0
	v_mfma_f32_32x32x16_bf16 v[82:97], v[8:11], v[118:121], v[82:97]
	ds_read_b128 v[4:7], v16 offset:64
	ds_read_b128 v[8:11], v16 offset:96
	s_waitcnt lgkmcnt(2)
	v_mfma_f32_32x32x16_bf16 v[98:113], v[12:15], v[118:121], v[98:113]
	s_waitcnt lgkmcnt(1)
	v_mfma_f32_32x32x16_bf16 v[82:97], v[4:7], v[122:125], v[82:97]
	ds_read_b128 v[4:7], v16 offset:4672
	ds_read_b128 v[12:15], v16 offset:4704
	s_waitcnt lgkmcnt(1)
	v_mfma_f32_32x32x16_bf16 v[98:113], v[4:7], v[122:125], v[98:113]
	v_mfma_f32_32x32x16_bf16 v[82:97], v[8:11], v[126:129], v[82:97]
	s_waitcnt lgkmcnt(0)
	v_mfma_f32_32x32x16_bf16 v[98:113], v[12:15], v[126:129], v[98:113]
	s_setprio 0
	v_add_u32_e32 v4, s8, v196
	v_cmp_le_i32_e32 vcc, s57, v193
	v_cmp_lt_i32_e64 s[6:7], s52, v4
	v_cmp_gt_i32_e64 s[4:5], s51, v4
	s_and_b64 s[6:7], vcc, s[6:7]
	v_add_f32_e32 v208, 0x41000000, v178
	s_and_saveexec_b64 s[28:29], s[6:7]
	s_xor_b64 s[6:7], exec, s[28:29]
	s_cbranch_execz .LBB0_2135
	s_cmp_eq_u64 s[6:7], 0
	s_cbranch_scc1 .Lfast_diff
	s_nop 1
	v_max_f32_e32 v4, v98, v98
	v_max_f32_e32 v5, v82, v82
	v_max_f32_e32 v4, v5, v4
	v_max3_f32 v4, v4, v83, v99
	s_nop 0
	v_max3_f32 v4, v4, v84, v100
	s_nop 0
	v_max3_f32 v4, v4, v85, v101
	s_nop 0
	v_max3_f32 v4, v4, v86, v102
	s_nop 0
	v_max3_f32 v4, v4, v87, v103
	s_nop 0
	v_max3_f32 v4, v4, v88, v104
	s_nop 0
	v_max3_f32 v4, v4, v89, v105
	s_nop 0
	v_max3_f32 v4, v4, v90, v106
	s_nop 0
	v_max3_f32 v4, v4, v91, v107
	s_nop 0
	v_max3_f32 v4, v4, v92, v108
	s_nop 0
	v_max3_f32 v4, v4, v93, v109
	s_nop 0
	v_max3_f32 v4, v4, v94, v110
	s_nop 0
	v_max3_f32 v4, v4, v95, v111
	s_nop 0
	v_max3_f32 v4, v4, v96, v112
	s_nop 0
	v_max3_f32 v4, v4, v97, v113
	s_nop 0
	v_mov_b32_e32 v5, v4
	s_nop 1
	v_permlane32_swap_b32_e32 v4, v5
	v_max_f32_e32 v5, v5, v5
	v_max_f32_e32 v4, v4, v4
	v_max_f32_e32 v4, v4, v5
	v_mul_f32_e32 v4, 0x3e38aa3b, v4
	v_cmp_gt_f32_e32 vcc, v4, v208
	s_nop 1
	v_cndmask_b32_e32 v207, v178, v4, vcc
	v_sub_f32_e32 v4, v178, v207
	v_exp_f32_e32 v178, v4
	s_nop 0
	v_cmp_neq_f32_e32 vcc, 1.0, v178
	s_cbranch_vccz .LBB0_2134
	v_pk_mul_f32 v[80:81], v[80:81], v[178:179] op_sel_hi:[1,0]
	v_pk_mul_f32 v[78:79], v[78:79], v[178:179] op_sel_hi:[1,0]
	v_pk_mul_f32 v[76:77], v[76:77], v[178:179] op_sel_hi:[1,0]
	v_pk_mul_f32 v[74:75], v[74:75], v[178:179] op_sel_hi:[1,0]
	v_pk_mul_f32 v[72:73], v[72:73], v[178:179] op_sel_hi:[1,0]
	v_pk_mul_f32 v[70:71], v[70:71], v[178:179] op_sel_hi:[1,0]
	v_pk_mul_f32 v[68:69], v[68:69], v[178:179] op_sel_hi:[1,0]
	v_pk_mul_f32 v[66:67], v[66:67], v[178:179] op_sel_hi:[1,0]
	v_pk_mul_f32 v[64:65], v[64:65], v[178:179] op_sel_hi:[1,0]
	v_pk_mul_f32 v[62:63], v[62:63], v[178:179] op_sel_hi:[1,0]
	v_pk_mul_f32 v[60:61], v[60:61], v[178:179] op_sel_hi:[1,0]
	v_pk_mul_f32 v[58:59], v[58:59], v[178:179] op_sel_hi:[1,0]
	v_pk_mul_f32 v[56:57], v[56:57], v[178:179] op_sel_hi:[1,0]
	v_pk_mul_f32 v[54:55], v[54:55], v[178:179] op_sel_hi:[1,0]
	v_pk_mul_f32 v[52:53], v[52:53], v[178:179] op_sel_hi:[1,0]
	v_pk_mul_f32 v[50:51], v[50:51], v[178:179] op_sel_hi:[1,0]
	v_pk_mul_f32 v[48:49], v[48:49], v[178:179] op_sel_hi:[1,0]
	v_pk_mul_f32 v[46:47], v[46:47], v[178:179] op_sel_hi:[1,0]
	v_pk_mul_f32 v[44:45], v[44:45], v[178:179] op_sel_hi:[1,0]
	v_pk_mul_f32 v[42:43], v[42:43], v[178:179] op_sel_hi:[1,0]
	v_pk_mul_f32 v[40:41], v[40:41], v[178:179] op_sel_hi:[1,0]
	v_pk_mul_f32 v[38:39], v[38:39], v[178:179] op_sel_hi:[1,0]
	v_pk_mul_f32 v[36:37], v[36:37], v[178:179] op_sel_hi:[1,0]
	v_pk_mul_f32 v[34:35], v[34:35], v[178:179] op_sel_hi:[1,0]
	v_pk_mul_f32 v[32:33], v[32:33], v[178:179] op_sel_hi:[1,0]
	v_pk_mul_f32 v[30:31], v[30:31], v[178:179] op_sel_hi:[1,0]
	v_pk_mul_f32 v[28:29], v[28:29], v[178:179] op_sel_hi:[1,0]
	v_pk_mul_f32 v[26:27], v[26:27], v[178:179] op_sel_hi:[1,0]
	v_pk_mul_f32 v[24:25], v[24:25], v[178:179] op_sel_hi:[1,0]
	v_pk_mul_f32 v[22:23], v[22:23], v[178:179] op_sel_hi:[1,0]
	v_pk_mul_f32 v[20:21], v[20:21], v[178:179] op_sel_hi:[1,0]
	v_pk_mul_f32 v[18:19], v[18:19], v[178:179] op_sel_hi:[1,0]
